# v55 + attention group B: LDS reads and staging writes ahead of the VALU max chains at the head of its barrier interval
# speedup vs baseline: 1.0023x; 1.0023x over previous
; __device__ __forceinline__ void partialSM(f32x16& p0, f32x16& p1, float& m_reg, float& mn, float& alpha) {
;   constexpr float C = SCALE * 1.4426950408889634f;
;   float pmax = p0[0]; for (int r = 1; r < 16; ++r) pmax = fmaxf(pmax, p0[r]); for (int r = 0; r < 16; ++r) pmax = fmaxf(pmax, p1[r]);
;   { auto rr = __builtin_amdgcn_permlane32_swap(__float_as_uint(pmax), __float_as_uint(pmax), false, false);
;     pmax = fmaxf(__uint_as_float(rr[0]), __uint_as_float(rr[1])); }
;   if (__builtin_expect(__all(pmax - m_reg <= THR / SCALE), 1)) { mn = m_reg; alpha = 1.f; }
;   else { mn = fmaxf(m_reg, pmax); alpha = __builtin_amdgcn_exp2f((m_reg - mn) * C); m_reg = mn; }
;   float mnC = -mn * C;
;   for (int r = 0; r < 16; ++r) p0[r] = fmaf(p0[r], C, mnC); for (int r = 0; r < 16; ++r) p1[r] = fmaf(p1[r], C, mnC);
;   for (int r = 0; r < 16; ++r) p0[r] = __builtin_amdgcn_exp2f(p0[r]);
; }
; __device__ __forceinline__ void qkt(f32x16& p0, f32x16& p1, const char* Kn, const char* Kp, const bf16x8* qr, int r32, int hi) {
;   p0 = f32x16{}; p1 = f32x16{};
; #pragma unroll
;   for (int d0 = 0; d0 < 8; ++d0) { int cb = (d0 * 16 + hi * 8) * 2;
;     bf16x8 b0 = *reinterpret_cast<const bf16x8*>(Kn + KSWZ(r32, cb));
;     bf16x8 b1 = *reinterpret_cast<const bf16x8*>(Kn + KSWZ(32 + r32, cb));
;     p0 = __builtin_amdgcn_mfma_f32_32x32x16_bf16(b0, qr[d0], p0, 0, 0, 0);
;     p1 = __builtin_amdgcn_mfma_f32_32x32x16_bf16(b1, qr[d0], p1, 0, 0, 0); }
; #pragma unroll
;   for (int d1 = 0; d1 < 4; ++d1) { int cb = (d1 * 16 + hi * 8) * 2;
;     bf16x8 b0 = *reinterpret_cast<const bf16x8*>(Kp + KPSWZ(r32, cb));
;     bf16x8 b1 = *reinterpret_cast<const bf16x8*>(Kp + KPSWZ(32 + r32, cb));
;     p0 = __builtin_amdgcn_mfma_f32_32x32x16_bf16(b0, qr[8 + d1], p0, 0, 0, 0);
;     p1 = __builtin_amdgcn_mfma_f32_32x32x16_bf16(b1, qr[8 + d1], p1, 0, 0, 0); }
; __device__ __forceinline__ void attn_unit(const bf16_t* __restrict__ Qb, const bf16_t* __restrict__ KV, const bf16_t* __restrict__ KP, bf16_t* __restrict__ Ob, ...
;     ...
;   for (int j = 1; j + 1 < NT; j += 2) {
;     SBAR(); qkt(pB0, pB1, KN_lds + SHM_KN, KP_lds + SHM_KP, qr, r32, hi);
;     finishSM(pA0, pA1, alA, l_reg, pa0, pa1, pa2, pa3); SBAR();
;     SLOAD(j + 1); SBAR();
;     pv_d0(o, vb0, pa0, pa1, pa2, pa3); partialSM(pB0, pB1, m_reg, mnB, alB);
;     __syncthreads(); SWAIT(); SWRITE(0);
;     RESC(alB); __syncthreads();
.Lpp_loop:
	s_barrier
	ds_read_b128 v[192:195], v160 offset:16384
	ds_read_b128 v[196:199], v160 offset:24576
	ds_read_b128 v[200:203], v161 offset:16384
	ds_read_b128 v[204:207], v161 offset:24576
	ds_read_b128 v[208:211], v162 offset:16384
	ds_read_b128 v[212:215], v162 offset:24576
	ds_read_b128 v[216:219], v163 offset:16384
	ds_read_b128 v[220:223], v163 offset:24576
	s_waitcnt vmcnt(0)
	ds_write_b128 v246, v[232:235]
	ds_write_b128 v246, v[236:239] offset:8192
	ds_write_b128 v248, v[240:243]
	ds_write_b128 v244, v[224:227]
	ds_write_b128 v244, v[228:231] offset:8192
	v_max3_f32 v250, v80, v81, v82
	v_max3_f32 v251, v83, v84, v85
	v_max3_f32 v250, v250, v86, v87
	v_max3_f32 v251, v251, v88, v89
	v_max3_f32 v250, v250, v90, v91
	v_max3_f32 v251, v251, v92, v93
	v_max3_f32 v250, v250, v94, v95
	v_max3_f32 v251, v251, v64, v65
	v_max3_f32 v250, v250, v66, v67
	v_max3_f32 v251, v251, v68, v69
	v_max3_f32 v250, v250, v70, v71
	v_max3_f32 v251, v251, v72, v73
	v_max3_f32 v250, v250, v74, v75
	v_max3_f32 v251, v251, v76, v77
	v_max3_f32 v250, v250, v78, v79
	v_max_f32_e32 v250, v250, v251
	v_cmp_lt_f32_e64 vcc, s64, |v250|
	global_load_dwordx4 v[232:235], v180, s[50:51]
	global_load_dwordx4 v[236:239], v180, s[52:53]
	global_load_dwordx4 v[224:227], v180, s[54:55] offset:256
	global_load_dwordx4 v[228:231], v180, s[56:57] offset:256
	global_load_dwordx4 v[240:243], v181, s[58:59]
	s_cmp_lg_u32 s62, 0
	s_cbranch_scc1 .Lpp_safe_Ba
	s_cbranch_vccnz .Lpp_sw_Ba
	v_exp_f32_e32 v80, v80
	v_exp_f32_e32 v81, v81
	v_exp_f32_e32 v82, v82
	v_exp_f32_e32 v83, v83
	v_exp_f32_e32 v84, v84
	v_exp_f32_e32 v85, v85
	v_exp_f32_e32 v86, v86
	v_exp_f32_e32 v87, v87
	v_exp_f32_e32 v88, v88
	v_exp_f32_e32 v89, v89
	v_exp_f32_e32 v90, v90
	v_exp_f32_e32 v91, v91
	v_exp_f32_e32 v92, v92
	v_exp_f32_e32 v93, v93
	v_exp_f32_e32 v94, v94
	v_exp_f32_e32 v95, v95
	v_exp_f32_e32 v64, v64
	v_exp_f32_e32 v65, v65
	v_exp_f32_e32 v66, v66
	v_exp_f32_e32 v67, v67
	v_exp_f32_e32 v68, v68
	v_exp_f32_e32 v69, v69
	v_exp_f32_e32 v70, v70
	v_exp_f32_e32 v71, v71
	v_exp_f32_e32 v72, v72
	v_exp_f32_e32 v73, v73
	v_exp_f32_e32 v74, v74
	v_exp_f32_e32 v75, v75
	v_exp_f32_e32 v76, v76
	v_exp_f32_e32 v77, v77
	v_exp_f32_e32 v78, v78
	v_exp_f32_e32 v79, v79
	v_add_f32_e32 v249, v80, v81
	v_add_f32_e32 v250, v82, v83
	v_add_f32_e32 v251, v84, v85
	v_add_f32_e32 v182, v86, v87
	v_add_f32_e32 v249, v88, v249
	v_add_f32_e32 v250, v89, v250
	v_add_f32_e32 v251, v90, v251
	v_add_f32_e32 v182, v91, v182
	v_add_f32_e32 v249, v92, v249
	v_add_f32_e32 v250, v93, v250
	v_add_f32_e32 v251, v94, v251
	v_add_f32_e32 v182, v95, v182
	v_add_f32_e32 v249, v64, v249
	v_add_f32_e32 v250, v65, v250
	v_add_f32_e32 v251, v66, v251
	v_add_f32_e32 v182, v67, v182
	v_add_f32_e32 v249, v68, v249
	v_add_f32_e32 v250, v69, v250
	v_add_f32_e32 v251, v70, v251
	v_add_f32_e32 v182, v71, v182
	v_add_f32_e32 v249, v72, v249
	v_add_f32_e32 v250, v73, v250
	v_add_f32_e32 v251, v74, v251
	v_add_f32_e32 v182, v75, v182
	v_add_f32_e32 v249, v76, v249
	v_add_f32_e32 v250, v77, v250
	v_add_f32_e32 v251, v78, v251
	v_add_f32_e32 v182, v79, v182
	v_add_f32_e32 v249, v249, v250
	v_add_f32_e32 v251, v251, v182
	v_add_f32_e32 v249, v249, v251
	v_add_f32_e32 v176, v176, v249
	v_cvt_pk_bf16_f32 v144, v80, v81
	v_cvt_pk_bf16_f32 v145, v82, v83
	v_cvt_pk_bf16_f32 v146, v84, v85
	v_cvt_pk_bf16_f32 v147, v86, v87
	v_cvt_pk_bf16_f32 v148, v88, v89
	v_cvt_pk_bf16_f32 v149, v90, v91
	v_cvt_pk_bf16_f32 v150, v92, v93
	v_cvt_pk_bf16_f32 v151, v94, v95
	v_cvt_pk_bf16_f32 v152, v64, v65
	v_cvt_pk_bf16_f32 v153, v66, v67
	v_cvt_pk_bf16_f32 v154, v68, v69
	v_cvt_pk_bf16_f32 v155, v70, v71
	v_cvt_pk_bf16_f32 v156, v72, v73
	v_cvt_pk_bf16_f32 v157, v74, v75
	v_cvt_pk_bf16_f32 v158, v76, v77
	v_cvt_pk_bf16_f32 v159, v78, v79
.Lpp_send_Ba:
	s_add_i32 s11, s11, 1
	s_waitcnt lgkmcnt(6)
	v_mfma_f32_32x32x16_bf16 v[80:95], v[192:195], v[136:139], 0
	v_mfma_f32_32x32x16_bf16 v[64:79], v[196:199], v[136:139], 0
	s_add_i32 s36, s35, 2
	s_min_u32 s36, s36, 67
	s_lshl_b32 s44, s36, 6
	ds_read_b128 v[192:195], v164 offset:16384
	ds_read_b128 v[196:199], v164 offset:24576
	s_waitcnt lgkmcnt(6)
	v_mfma_f32_32x32x16_bf16 v[80:95], v[200:203], v[132:135], v[80:95]
	v_mfma_f32_32x32x16_bf16 v[64:79], v[204:207], v[132:135], v[64:79]
	s_add_i32 s45, s31, s44
	s_add_i32 s46, s24, s44
	s_add_i32 s46, s46, 0xffffff00
	ds_read_b128 v[200:203], v165 offset:16384
	ds_read_b128 v[204:207], v165 offset:24576
	s_waitcnt lgkmcnt(6)
	v_mfma_f32_32x32x16_bf16 v[80:95], v[208:211], v[128:131], v[80:95]
	v_mfma_f32_32x32x16_bf16 v[64:79], v[212:215], v[128:131], v[64:79]
	s_cmp_lt_u32 s36, 4
	s_cselect_b32 s36, s45, s46
	s_add_i32 s37, s35, 1
	ds_read_b128 v[208:211], v166 offset:16384
	ds_read_b128 v[212:215], v166 offset:24576
	s_waitcnt lgkmcnt(6)
	v_mfma_f32_32x32x16_bf16 v[80:95], v[216:219], v[124:127], v[80:95]
	v_mfma_f32_32x32x16_bf16 v[64:79], v[220:223], v[124:127], v[64:79]
	s_min_u32 s37, s37, 67
	s_lshl_b32 s44, s37, 6
	s_add_i32 s45, s31, s44
	ds_read_b128 v[216:219], v167 offset:16384
	ds_read_b128 v[220:223], v167 offset:24576
	s_waitcnt lgkmcnt(6)
	v_mfma_f32_32x32x16_bf16 v[80:95], v[192:195], v[120:123], v[80:95]
	v_mfma_f32_32x32x16_bf16 v[64:79], v[196:199], v[120:123], v[64:79]
	s_add_i32 s46, s24, s44
	s_add_i32 s46, s46, 0xffffff00
	s_cmp_lt_u32 s37, 4
	ds_read_b128 v[192:195], v168 offset:8192
	ds_read_b128 v[196:199], v168 offset:12288
	s_waitcnt lgkmcnt(6)
	v_mfma_f32_32x32x16_bf16 v[80:95], v[200:203], v[140:143], v[80:95]
	v_mfma_f32_32x32x16_bf16 v[64:79], v[204:207], v[140:143], v[64:79]
	s_cselect_b32 s37, s45, s46
	s_add_i32 s35, s35, 1
	s_lshl_b32 s44, s36, 12
	ds_read_b128 v[200:203], v169 offset:8192
	ds_read_b128 v[204:207], v169 offset:12288
	s_waitcnt lgkmcnt(6)
; #define SBAR() __builtin_amdgcn_sched_barrier(0)
; __device__ __forceinline__ void qkt(f32x16& p0, f32x16& p1, const char* Kn, const char* Kp, const bf16x8* qr, int r32, int hi) {
;   p0 = f32x16{}; p1 = f32x16{};
; #pragma unroll
;   for (int d0 = 0; d0 < 8; ++d0) { int cb = (d0 * 16 + hi * 8) * 2;
;     bf16x8 b0 = *reinterpret_cast<const bf16x8*>(Kn + KSWZ(r32, cb));
;     bf16x8 b1 = *reinterpret_cast<const bf16x8*>(Kn + KSWZ(32 + r32, cb));
;     p0 = __builtin_amdgcn_mfma_f32_32x32x16_bf16(b0, qr[d0], p0, 0, 0, 0);
;     p1 = __builtin_amdgcn_mfma_f32_32x32x16_bf16(b1, qr[d0], p1, 0, 0, 0); }
; #pragma unroll
;   for (int d1 = 0; d1 < 4; ++d1) { int cb = (d1 * 16 + hi * 8) * 2;
;     bf16x8 b0 = *reinterpret_cast<const bf16x8*>(Kp + KPSWZ(r32, cb));
;     bf16x8 b1 = *reinterpret_cast<const bf16x8*>(Kp + KPSWZ(32 + r32, cb));
;     p0 = __builtin_amdgcn_mfma_f32_32x32x16_bf16(b0, qr[8 + d1], p0, 0, 0, 0);
;     p1 = __builtin_amdgcn_mfma_f32_32x32x16_bf16(b1, qr[8 + d1], p1, 0, 0, 0); }
; template <int D0> __device__ __forceinline__ void pv_one(f32x16& od, int vb, bf16x8 pa0, bf16x8 pa1, bf16x8 pa2, bf16x8 pa3) {
;   const s16x4 l0 = tr_read<v_rd_off(D0, 0, 0)>(vb), h0 = tr_read<v_rd_off(D0, 0, 1)>(vb), l1 = tr_read<v_rd_off(D0, 1, 0)>(vb), h1 = tr_read<v_rd_off(D0, 1, 1)>(vb);
;   const s16x4 l2 = tr_read<v_rd_off(D0, 2, 0)>(vb), h2 = tr_read<v_rd_off(D0, 2, 1)>(vb), l3 = tr_read<v_rd_off(D0, 3, 0)>(vb), h3 = tr_read<v_rd_off(D0, 3, 1)>(vb);
;   asm volatile("s_waitcnt lgkmcnt(0)" ::: "memory"); SBAR();
;     ...
;   od = __builtin_amdgcn_mfma_f32_32x32x16_bf16(pa0, PK(l0, h0), od, 0, 0, 0);
;   od = __builtin_amdgcn_mfma_f32_32x32x16_bf16(pa1, PK(l1, h1), od, 0, 0, 0);
;   od = __builtin_amdgcn_mfma_f32_32x32x16_bf16(pa2, PK(l2, h2), od, 0, 0, 0);
;   od = __builtin_amdgcn_mfma_f32_32x32x16_bf16(pa3, PK(l3, h3), od, 0, 0, 0);
;     ...
; }
; __device__ __forceinline__ void pv_d0(f32x16* o, int vb, bf16x8 pa0, bf16x8 pa1, bf16x8 pa2, bf16x8 pa3) {
;   pv_one<0>(o[0], vb, pa0, pa1, pa2, pa3); pv_one<1>(o[1], vb, pa0, pa1, pa2, pa3); pv_one<2>(o[2], vb, pa0, pa1, pa2, pa3); pv_one<3>(o[3], vb, pa0, pa1, pa2, pa3);
	v_mfma_f32_32x32x16_bf16 v[80:95], v[208:211], v[116:119], v[80:95]
	v_mfma_f32_32x32x16_bf16 v[64:79], v[212:215], v[116:119], v[64:79]
	s_add_u32 s50, s47, s44
	s_addc_u32 s51, s63, 0
	s_add_u32 s52, s50, 0x20000
	ds_read_b128 v[208:211], v170 offset:8192
	ds_read_b128 v[212:215], v170 offset:12288
	s_waitcnt lgkmcnt(6)
	v_mfma_f32_32x32x16_bf16 v[80:95], v[216:219], v[112:115], v[80:95]
	v_mfma_f32_32x32x16_bf16 v[64:79], v[220:223], v[112:115], v[64:79]
	s_addc_u32 s53, s51, 0
	s_lshl_b32 s44, s37, 12
	s_add_u32 s54, s47, s44
	ds_read_b128 v[216:219], v171 offset:8192
	ds_read_b128 v[220:223], v171 offset:12288
	s_waitcnt lgkmcnt(6)
	v_mfma_f32_32x32x16_bf16 v[80:95], v[192:195], v[108:111], v[80:95]
	v_mfma_f32_32x32x16_bf16 v[64:79], v[196:199], v[108:111], v[64:79]
	s_addc_u32 s55, s63, 0
	s_add_u32 s56, s54, 0x20000
	s_addc_u32 s57, s55, 0
	ds_read_b64_tr_b16 v[192:193], v174 offset:0
	ds_read_b64_tr_b16 v[194:195], v174 offset:2048
	ds_read_b64_tr_b16 v[196:197], v174 offset:4096
	ds_read_b64_tr_b16 v[198:199], v174 offset:6144
	s_waitcnt lgkmcnt(8)
	v_mfma_f32_32x32x16_bf16 v[80:95], v[200:203], v[104:107], v[80:95]
	v_mfma_f32_32x32x16_bf16 v[64:79], v[204:207], v[104:107], v[64:79]
	s_lshl_b32 s44, s36, 10
	s_add_u32 s58, s60, s44
	s_addc_u32 s59, s61, 0
	ds_read_b64_tr_b16 v[200:201], v174 offset:8192
	ds_read_b64_tr_b16 v[202:203], v174 offset:10240
	ds_read_b64_tr_b16 v[204:205], v174 offset:12288
	ds_read_b64_tr_b16 v[206:207], v174 offset:14336
	s_waitcnt lgkmcnt(10)
	v_mfma_f32_32x32x16_bf16 v[80:95], v[208:211], v[100:103], v[80:95]
	v_mfma_f32_32x32x16_bf16 v[64:79], v[212:215], v[100:103], v[64:79]
	ds_read_b64_tr_b16 v[208:209], v174 offset:512
	ds_read_b64_tr_b16 v[210:211], v174 offset:2560
	ds_read_b64_tr_b16 v[212:213], v174 offset:4608
	ds_read_b64_tr_b16 v[214:215], v174 offset:6656
	s_waitcnt lgkmcnt(12)
	v_mfma_f32_32x32x16_bf16 v[80:95], v[216:219], v[96:99], v[80:95]
	v_mfma_f32_32x32x16_bf16 v[64:79], v[220:223], v[96:99], v[64:79]
	ds_read_b64_tr_b16 v[216:217], v174 offset:8704
	ds_read_b64_tr_b16 v[218:219], v174 offset:10752
	ds_read_b64_tr_b16 v[220:221], v174 offset:12800
	ds_read_b64_tr_b16 v[222:223], v174 offset:14848
	s_waitcnt lgkmcnt(12)
	v_mfma_f32_32x32x16_bf16 v[0:15], v[144:147], v[192:195], v[0:15]
	ds_read_b64_tr_b16 v[192:193], v174 offset:1024
	ds_read_b64_tr_b16 v[194:195], v174 offset:3072
	v_mfma_f32_32x32x16_bf16 v[0:15], v[148:151], v[196:199], v[0:15]
	ds_read_b64_tr_b16 v[196:197], v174 offset:5120
	ds_read_b64_tr_b16 v[198:199], v174 offset:7168
	s_waitcnt lgkmcnt(12)
	v_mfma_f32_32x32x16_bf16 v[0:15], v[152:155], v[200:203], v[0:15]
	ds_read_b64_tr_b16 v[200:201], v174 offset:9216
	ds_read_b64_tr_b16 v[202:203], v174 offset:11264
	v_mfma_f32_32x32x16_bf16 v[0:15], v[156:159], v[204:207], v[0:15]
	ds_read_b64_tr_b16 v[204:205], v174 offset:13312
	ds_read_b64_tr_b16 v[206:207], v174 offset:15360
	s_waitcnt lgkmcnt(12)
	v_mfma_f32_32x32x16_bf16 v[48:63], v[144:147], v[208:211], v[48:63]
	ds_read_b64_tr_b16 v[208:209], v174 offset:1536
	ds_read_b64_tr_b16 v[210:211], v174 offset:3584
	v_mfma_f32_32x32x16_bf16 v[48:63], v[148:151], v[212:215], v[48:63]
	ds_read_b64_tr_b16 v[212:213], v174 offset:5632
	ds_read_b64_tr_b16 v[214:215], v174 offset:7680
	s_waitcnt lgkmcnt(12)
	v_mfma_f32_32x32x16_bf16 v[48:63], v[152:155], v[216:219], v[48:63]
	ds_read_b64_tr_b16 v[216:217], v174 offset:9728
	ds_read_b64_tr_b16 v[218:219], v174 offset:11776
	v_mfma_f32_32x32x16_bf16 v[48:63], v[156:159], v[220:223], v[48:63]
	ds_read_b64_tr_b16 v[220:221], v174 offset:13824
	ds_read_b64_tr_b16 v[222:223], v174 offset:15872
	s_waitcnt lgkmcnt(12)
	v_mfma_f32_32x32x16_bf16 v[32:47], v[144:147], v[192:195], v[32:47]
	v_mfma_f32_32x32x16_bf16 v[32:47], v[148:151], v[196:199], v[32:47]
	s_waitcnt lgkmcnt(8)
	v_mfma_f32_32x32x16_bf16 v[32:47], v[152:155], v[200:203], v[32:47]
	v_mfma_f32_32x32x16_bf16 v[32:47], v[156:159], v[204:207], v[32:47]
	s_waitcnt lgkmcnt(4)
	v_mfma_f32_32x32x16_bf16 v[16:31], v[144:147], v[208:211], v[16:31]
	v_mfma_f32_32x32x16_bf16 v[16:31], v[148:151], v[212:215], v[16:31]
	s_waitcnt lgkmcnt(0)
	v_mfma_f32_32x32x16_bf16 v[16:31], v[152:155], v[216:219], v[16:31]
	v_mfma_f32_32x32x16_bf16 v[16:31], v[156:159], v[220:223], v[16:31]
	s_barrier
; #define SBAR() __builtin_amdgcn_sched_barrier(0)
; #define SLOAD(j) do { const int r0_ = TROW(j); const bf16_t* a_ = KVh + (size_t)(r0_ + sr) * LDKV + sc; const bf16_t* b_ = KVh + (size_t)(r0_ + 32 + sr) * LDKV + sc; \
;     vs0 = ld8(a_ + 128); vs1 = ld8(b_ + 128); ks0 = ld8(a_); ks1 = ld8(b_); kp0 = ld8(KPh + (size_t)(r0_ + pr) * LDKP + pc); } while (0)
; #define SWRITE(b) do { *(bf16x8*)(V_lds + (b) * SHM_V + vst0) = vs0; *(bf16x8*)(V_lds + (b) * SHM_V + vst1) = vs1; const int kc = sc * 2; \
;     *(bf16x8*)(KN_lds + (b) * SHM_KN + KSWZ(sr, kc)) = ks0; *(bf16x8*)(KN_lds + (b) * SHM_KN + KSWZ(32 + sr, kc)) = ks1; \
;     *(bf16x8*)(KP_lds + (b) * SHM_KP + KPSWZ(pr, pc * 2)) = kp0; } while (0)
; #define SWAIT() asm volatile("s_waitcnt vmcnt(0)" ::: "memory")
; #define RESC(a) do { if (__any((a) < 1.f)) { if (hi == 0) al_l[r32] = (a); asm volatile("s_waitcnt lgkmcnt(0)" ::: "memory"); \
;     for (int d = 0; d < 4; ++d) for (int r = 0; r < 16; ++r) o[d][r] *= al_l[crow(r, hi)]; } } while (0)
; __device__ __forceinline__ void partialSM(f32x16& p0, f32x16& p1, float& m_reg, float& mn, float& alpha) {
;   constexpr float C = SCALE * 1.4426950408889634f;
;   float pmax = p0[0]; for (int r = 1; r < 16; ++r) pmax = fmaxf(pmax, p0[r]); for (int r = 0; r < 16; ++r) pmax = fmaxf(pmax, p1[r]);
;   { auto rr = __builtin_amdgcn_permlane32_swap(__float_as_uint(pmax), __float_as_uint(pmax), false, false);
;     pmax = fmaxf(__uint_as_float(rr[0]), __uint_as_float(rr[1])); }
;   if (__builtin_expect(__all(pmax - m_reg <= THR / SCALE), 1)) { mn = m_reg; alpha = 1.f; }
;   else { mn = fmaxf(m_reg, pmax); alpha = __builtin_amdgcn_exp2f((m_reg - mn) * C); m_reg = mn; }
;   float mnC = -mn * C;
;   for (int r = 0; r < 16; ++r) p0[r] = fmaf(p0[r], C, mnC); for (int r = 0; r < 16; ++r) p1[r] = fmaf(p1[r], C, mnC);
;   for (int r = 0; r < 16; ++r) p0[r] = __builtin_amdgcn_exp2f(p0[r]);
; }
; __device__ __forceinline__ void attn_unit(const bf16_t* __restrict__ Qb, const bf16_t* __restrict__ KV, const bf16_t* __restrict__ KP, bf16_t* __restrict__ Ob, ...
;     ...
;     SBAR(); qkt(pA0, pA1, KN_lds, KP_lds, qr, r32, hi);
;     finishSM(pB0, pB1, alB, l_reg, pa0, pa1, pa2, pa3); SBAR();
;     SLOAD(j + 2); SBAR();
;     pv_d0(o, vb0 + SHM_V, pa0, pa1, pa2, pa3); partialSM(pA0, pA1, m_reg, mnA, alA);
;     __syncthreads(); SWAIT(); SWRITE(1);
;     RESC(alA); __syncthreads();
	ds_read_b128 v[192:195], v160
	ds_read_b128 v[196:199], v160 offset:8192
	ds_read_b128 v[200:203], v161
	ds_read_b128 v[204:207], v161 offset:8192
	ds_read_b128 v[208:211], v162
	ds_read_b128 v[212:215], v162 offset:8192
	ds_read_b128 v[216:219], v163
	ds_read_b128 v[220:223], v163 offset:8192
	s_waitcnt vmcnt(0)
	ds_write_b128 v247, v[232:235]
	ds_write_b128 v247, v[236:239] offset:8192
	ds_write_b128 v183, v[240:243]
	ds_write_b128 v245, v[224:227]
	ds_write_b128 v245, v[228:231] offset:8192
	v_max3_f32 v250, v80, v81, v82
	v_max3_f32 v251, v83, v84, v85
	v_max3_f32 v250, v250, v86, v87
	v_max3_f32 v251, v251, v88, v89
	v_max3_f32 v250, v250, v90, v91
	v_max3_f32 v251, v251, v92, v93
	v_max3_f32 v250, v250, v94, v95
	v_max3_f32 v251, v251, v64, v65
	v_max3_f32 v250, v250, v66, v67
	v_max3_f32 v251, v251, v68, v69
	v_max3_f32 v250, v250, v70, v71
	v_max3_f32 v251, v251, v72, v73
	v_max3_f32 v250, v250, v74, v75
	v_max3_f32 v251, v251, v76, v77
	v_max3_f32 v250, v250, v78, v79
	v_max_f32_e32 v250, v250, v251
	v_cmp_lt_f32_e64 vcc, s64, |v250|
	global_load_dwordx4 v[232:235], v180, s[50:51]
	global_load_dwordx4 v[236:239], v180, s[52:53]
	global_load_dwordx4 v[224:227], v180, s[54:55] offset:256
	global_load_dwordx4 v[228:231], v180, s[56:57] offset:256
	global_load_dwordx4 v[240:243], v181, s[58:59]
	s_cmp_lg_u32 s62, 0
	s_cbranch_scc1 .Lpp_safe_Bb
	s_cbranch_vccnz .Lpp_sw_Bb
	v_exp_f32_e32 v80, v80
	v_exp_f32_e32 v81, v81
	v_exp_f32_e32 v82, v82
	v_exp_f32_e32 v83, v83
	v_exp_f32_e32 v84, v84
	v_exp_f32_e32 v85, v85
	v_exp_f32_e32 v86, v86
	v_exp_f32_e32 v87, v87
	v_exp_f32_e32 v88, v88
	v_exp_f32_e32 v89, v89
	v_exp_f32_e32 v90, v90
	v_exp_f32_e32 v91, v91
	v_exp_f32_e32 v92, v92
	v_exp_f32_e32 v93, v93
	v_exp_f32_e32 v94, v94
	v_exp_f32_e32 v95, v95
	v_exp_f32_e32 v64, v64
	v_exp_f32_e32 v65, v65
	v_exp_f32_e32 v66, v66
	v_exp_f32_e32 v67, v67
	v_exp_f32_e32 v68, v68
	v_exp_f32_e32 v69, v69
	v_exp_f32_e32 v70, v70
	v_exp_f32_e32 v71, v71
	v_exp_f32_e32 v72, v72
	v_exp_f32_e32 v73, v73
	v_exp_f32_e32 v74, v74
	v_exp_f32_e32 v75, v75
	v_exp_f32_e32 v76, v76
	v_exp_f32_e32 v77, v77
	v_exp_f32_e32 v78, v78
	v_exp_f32_e32 v79, v79
	v_add_f32_e32 v249, v80, v81
	v_add_f32_e32 v250, v82, v83
	v_add_f32_e32 v251, v84, v85
	v_add_f32_e32 v182, v86, v87
	v_add_f32_e32 v249, v88, v249
	v_add_f32_e32 v250, v89, v250
	v_add_f32_e32 v251, v90, v251
	v_add_f32_e32 v182, v91, v182
	v_add_f32_e32 v249, v92, v249
	v_add_f32_e32 v250, v93, v250
	v_add_f32_e32 v251, v94, v251
	v_add_f32_e32 v182, v95, v182
	v_add_f32_e32 v249, v64, v249
	v_add_f32_e32 v250, v65, v250
	v_add_f32_e32 v251, v66, v251
	v_add_f32_e32 v182, v67, v182
	v_add_f32_e32 v249, v68, v249
	v_add_f32_e32 v250, v69, v250
	v_add_f32_e32 v251, v70, v251
	v_add_f32_e32 v182, v71, v182
	v_add_f32_e32 v249, v72, v249
	v_add_f32_e32 v250, v73, v250
	v_add_f32_e32 v251, v74, v251
	v_add_f32_e32 v182, v75, v182
	v_add_f32_e32 v249, v76, v249
	v_add_f32_e32 v250, v77, v250
	v_add_f32_e32 v251, v78, v251
	v_add_f32_e32 v182, v79, v182
	v_add_f32_e32 v249, v249, v250
	v_add_f32_e32 v251, v251, v182
	v_add_f32_e32 v249, v249, v251
	v_add_f32_e32 v176, v176, v249
	v_cvt_pk_bf16_f32 v144, v80, v81
	v_cvt_pk_bf16_f32 v145, v82, v83
	v_cvt_pk_bf16_f32 v146, v84, v85
	v_cvt_pk_bf16_f32 v147, v86, v87
	v_cvt_pk_bf16_f32 v148, v88, v89
	v_cvt_pk_bf16_f32 v149, v90, v91
	v_cvt_pk_bf16_f32 v150, v92, v93
	v_cvt_pk_bf16_f32 v151, v94, v95
	v_cvt_pk_bf16_f32 v152, v64, v65
	v_cvt_pk_bf16_f32 v153, v66, v67
	v_cvt_pk_bf16_f32 v154, v68, v69
	v_cvt_pk_bf16_f32 v155, v70, v71
	v_cvt_pk_bf16_f32 v156, v72, v73
	v_cvt_pk_bf16_f32 v157, v74, v75
	v_cvt_pk_bf16_f32 v158, v76, v77
	v_cvt_pk_bf16_f32 v159, v78, v79
